# ph0 pool-weight items: w_pool block copied to LDS once per WG, rows read by broadcast ds_read_b128 (was ~130 same-address vector loads per 8 columns)
# baseline (speedup 1.0000x reference)
.LBB0_694:
	s_ashr_i32 s12, s8, 6
	s_ashr_i32 s13, s12, 31
	s_mul_i32 s0, s12, 0x3680000
	s_mul_hi_i32 s1, s12, 0x3680000
	s_add_u32 s0, s78, s0
	s_addc_u32 s1, s79, s1
	s_lshl_b32 s4, s8, 6
	s_lshl_b32 s6, s8, 2
	s_and_b32 s4, s4, 0x3c0
	s_and_b32 s9, s6, 0xc0
	v_or_b32_e32 v44, s4, v83
	s_lshl_b64 s[4:5], s[12:13], 16
	s_lshl_b32 s10, s9, 8
	s_waitcnt lgkmcnt(1)
	v_readfirstlane_b32 s14, v2
	s_lshl_b64 s[6:7], s[12:13], 10
	v_readfirstlane_b32 s11, v3
	s_add_u32 s6, s14, s6
	s_addc_u32 s7, s11, s7
	s_lshl_b32 s11, s9, 2
	s_waitcnt lgkmcnt(0)
	v_readfirstlane_b32 s15, v86
	s_lshl_b64 s[12:13], s[12:13], 20
	v_readfirstlane_b32 s14, v87
	s_add_u32 s12, s15, s12
	s_addc_u32 s13, s14, s13
	s_lshl_b32 s14, s9, 12
	s_add_u32 s12, s12, s14
	s_addc_u32 s13, s13, 0
	v_lshlrev_b32_e32 v144, 2, v44
	v_lshl_add_u64 v[40:41], s[12:13], 0, v[144:145]
	v_add_co_u32_e32 v4, vcc, s68, v40
	v_mov_b32_e32 v45, s11
	s_nop 0
	v_addc_co_u32_e32 v5, vcc, 0, v41, vcc
	s_movk_i32 s11, 0x4000
	v_add_co_u32_e32 v6, vcc, s11, v40
	s_mov_b32 s11, 0x8000
	s_nop 0
	v_addc_co_u32_e32 v7, vcc, 0, v41, vcc
	v_add_co_u32_e32 v24, vcc, s19, v40
	global_load_dwordx4 v[8:11], v45, s[6:7] offset:48
	global_load_dwordx4 v[12:15], v45, s[6:7] offset:32
	global_load_dwordx4 v[16:19], v45, s[6:7] offset:16
	global_load_dwordx4 v[20:23], v45, s[6:7]
	v_addc_co_u32_e32 v25, vcc, 0, v41, vcc
	global_load_dword v50, v144, s[12:13]
	global_load_dword v51, v[4:5], off offset:-4096
	global_load_dword v52, v[4:5], off
	global_load_dword v53, v[6:7], off offset:-4096
	global_load_dword v54, v[6:7], off
	global_load_dword v55, v[24:25], off offset:-4096
	global_load_dword v56, v[24:25], off
	v_add_co_u32_e32 v4, vcc, s11, v40
	s_mov_b32 s11, 0xa000
	s_nop 0
	v_addc_co_u32_e32 v5, vcc, 0, v41, vcc
	v_add_co_u32_e32 v6, vcc, s11, v40
	s_mov_b32 s11, 0xe000
	s_nop 0
	v_addc_co_u32_e32 v7, vcc, 0, v41, vcc
	v_add_co_u32_e32 v24, vcc, s22, v40
	s_waitcnt vmcnt(6)
	v_mul_f32_e32 v88, v50, v20
	v_addc_co_u32_e32 v25, vcc, 0, v41, vcc
	v_add_co_u32_e32 v26, vcc, s11, v40
	s_mov_b32 s11, 0x10000
	s_nop 0
	v_addc_co_u32_e32 v27, vcc, 0, v41, vcc
	global_load_dword v57, v[4:5], off offset:-4096
	global_load_dword v58, v[4:5], off
	global_load_dword v59, v[6:7], off offset:-4096
	global_load_dword v60, v[6:7], off
	global_load_dword v61, v[24:25], off offset:-4096
	global_load_dword v62, v[24:25], off
	global_load_dword v63, v[26:27], off offset:-4096
	global_load_dword v64, v[26:27], off
	v_add_co_u32_e32 v24, vcc, s11, v40
	s_mov_b32 s11, 0x14000
	s_nop 0
	v_addc_co_u32_e32 v25, vcc, 0, v41, vcc
	v_add_co_u32_e32 v26, vcc, s59, v40
	global_load_dwordx4 v[4:7], v45, s[6:7] offset:112
	global_load_dwordx4 v[28:31], v45, s[6:7] offset:96
	global_load_dwordx4 v[32:35], v45, s[6:7] offset:80
	global_load_dwordx4 v[36:39], v45, s[6:7] offset:64
	v_addc_co_u32_e32 v27, vcc, 0, v41, vcc
	v_add_co_u32_e32 v42, vcc, s11, v40
	s_mov_b32 s11, 0x16000
	s_nop 0
	v_addc_co_u32_e32 v43, vcc, 0, v41, vcc
	v_add_co_u32_e32 v46, vcc, s11, v40
	s_mov_b32 s11, 0x18000
	s_nop 0
	v_addc_co_u32_e32 v47, vcc, 0, v41, vcc
	global_load_dword v65, v[24:25], off offset:-4096
	global_load_dword v66, v[24:25], off
	global_load_dword v67, v[26:27], off offset:-4096
	global_load_dword v68, v[26:27], off
	global_load_dword v69, v[42:43], off offset:-4096
	global_load_dword v70, v[42:43], off
	global_load_dword v71, v[46:47], off offset:-4096
	global_load_dword v72, v[46:47], off
	v_add_co_u32_e32 v24, vcc, s11, v40
	s_mov_b32 s11, 0x1a000
	s_nop 0
	v_addc_co_u32_e32 v25, vcc, 0, v41, vcc
	v_add_co_u32_e32 v26, vcc, s11, v40
	s_mov_b32 s11, 0x1c000
	s_nop 0
	v_addc_co_u32_e32 v27, vcc, 0, v41, vcc
	v_add_co_u32_e32 v42, vcc, s11, v40
	s_mov_b32 s11, 0x1e000
	s_nop 0
	v_addc_co_u32_e32 v43, vcc, 0, v41, vcc
	v_add_co_u32_e32 v46, vcc, s11, v40
	s_mov_b32 s11, 0x22000
	s_nop 0
	v_addc_co_u32_e32 v47, vcc, 0, v41, vcc
	global_load_dword v73, v[24:25], off offset:-4096
	global_load_dword v74, v[24:25], off
	global_load_dword v75, v[26:27], off offset:-4096
	global_load_dword v76, v[26:27], off
	global_load_dword v77, v[42:43], off offset:-4096
	global_load_dword v78, v[42:43], off
	global_load_dword v79, v[46:47], off offset:-4096
	global_load_dword v80, v[46:47], off
	v_add_co_u32_e32 v46, vcc, s95, v40
	global_load_dwordx4 v[24:27], v45, s[6:7] offset:128
	s_nop 0
	v_addc_co_u32_e32 v47, vcc, 0, v41, vcc
	v_add_co_u32_e32 v48, vcc, s11, v40
	s_mov_b32 s11, 0x26000
	s_nop 0
	v_addc_co_u32_e32 v49, vcc, 0, v41, vcc
	v_add_co_u32_e32 v42, vcc, s67, v40
	s_waitcnt vmcnt(31)
	v_mul_f32_e32 v96, v54, v16
	v_addc_co_u32_e32 v43, vcc, 0, v41, vcc
	global_load_dword v81, v[46:47], off offset:-4096
	global_load_dword v82, v[46:47], off
	global_load_dword v85, v[48:49], off offset:-4096
	s_nop 0
	global_load_dword v48, v[48:49], off
	s_nop 0
	global_load_dword v49, v[42:43], off offset:-4096
	v_add_co_u32_e32 v46, vcc, s75, v40
	s_waitcnt vmcnt(35)
	v_mul_f32_e32 v98, v55, v17
	v_addc_co_u32_e32 v47, vcc, 0, v41, vcc
	global_load_dword v46, v[46:47], off
	s_waitcnt vmcnt(35)
	v_mul_f32_e32 v100, v56, v18
	v_mul_f32_e32 v90, v51, v21
	v_mul_f32_e32 v92, v52, v22
	v_mul_f32_e32 v94, v53, v23
	v_mov_b32_e32 v89, v88
	v_mov_b32_e32 v91, v90
	v_mov_b32_e32 v93, v92
	v_mov_b32_e32 v95, v94
	s_waitcnt vmcnt(34)
	v_mul_f32_e32 v102, v57, v19
	s_waitcnt vmcnt(33)
	v_mul_f32_e32 v104, v58, v12
	s_waitcnt vmcnt(32)
	v_mul_f32_e32 v106, v59, v13
	s_waitcnt vmcnt(31)
	v_mul_f32_e32 v108, v60, v14
	s_waitcnt vmcnt(30)
	v_mul_f32_e32 v110, v61, v15
	s_waitcnt vmcnt(29)
	v_mul_f32_e32 v112, v62, v8
	s_waitcnt vmcnt(28)
	v_mul_f32_e32 v114, v63, v9
	s_waitcnt vmcnt(27)
	v_mul_f32_e32 v116, v64, v10
	v_mov_b32_e32 v109, v108
	v_mov_b32_e32 v111, v110
	v_mov_b32_e32 v113, v112
	v_mov_b32_e32 v115, v114
	v_mov_b32_e32 v117, v116
	v_mov_b32_e32 v107, v106
	v_mov_b32_e32 v97, v96
	v_mov_b32_e32 v99, v98
	v_mov_b32_e32 v101, v100
	v_mov_b32_e32 v103, v102
	v_mov_b32_e32 v105, v104
	s_waitcnt vmcnt(22)
	v_mul_f32_e32 v118, v65, v11
	s_waitcnt vmcnt(21)
	v_mul_f32_e32 v120, v66, v36
	s_waitcnt vmcnt(20)
	v_mul_f32_e32 v122, v67, v37
	s_waitcnt vmcnt(19)
	v_mul_f32_e32 v124, v68, v38
	s_waitcnt vmcnt(18)
	v_mul_f32_e32 v126, v69, v39
	s_waitcnt vmcnt(17)
	v_mul_f32_e32 v128, v70, v32
	s_waitcnt vmcnt(16)
	v_mul_f32_e32 v130, v71, v33
	s_waitcnt vmcnt(15)
	v_mul_f32_e32 v132, v72, v34
	v_mov_b32_e32 v131, v130
	v_mov_b32_e32 v133, v132
	v_mov_b32_e32 v129, v128
	v_mov_b32_e32 v119, v118
	v_mov_b32_e32 v121, v120
	v_mov_b32_e32 v123, v122
	v_mov_b32_e32 v125, v124
	v_mov_b32_e32 v127, v126
	s_waitcnt vmcnt(14)
	v_mul_f32_e32 v134, v73, v35
	s_waitcnt vmcnt(13)
	v_mul_f32_e32 v136, v74, v28
	s_waitcnt vmcnt(12)
	v_mul_f32_e32 v138, v75, v29
	s_waitcnt vmcnt(11)
	v_mul_f32_e32 v140, v76, v30
	s_waitcnt vmcnt(10)
	v_mul_f32_e32 v142, v77, v31
	s_waitcnt vmcnt(9)
	v_mul_f32_e32 v146, v78, v4
	v_add_co_u32_e32 v4, vcc, s11, v40
	s_waitcnt vmcnt(8)
	v_mul_f32_e32 v148, v79, v5
	v_addc_co_u32_e32 v5, vcc, 0, v41, vcc
	s_mov_b32 s11, 0x28000
	global_load_dword v8, v[42:43], off
	global_load_dword v9, v[4:5], off offset:-4096
	global_load_dword v10, v[4:5], off
	v_add_co_u32_e32 v4, vcc, s11, v40
	s_mov_b32 s11, 0x2a000
	s_nop 0
	v_addc_co_u32_e32 v5, vcc, 0, v41, vcc
	global_load_dword v11, v[4:5], off offset:-4096
	global_load_dword v12, v[4:5], off
	v_add_co_u32_e32 v4, vcc, s11, v40
	s_mov_b32 s11, 0x2c000
	s_nop 0
	v_addc_co_u32_e32 v5, vcc, 0, v41, vcc
	global_load_dword v13, v[4:5], off offset:-4096
	global_load_dword v14, v[4:5], off
	v_add_co_u32_e32 v4, vcc, s11, v40
	s_mov_b32 s11, 0x2e000
	s_nop 0
	v_addc_co_u32_e32 v5, vcc, 0, v41, vcc
	global_load_dword v15, v[4:5], off offset:-4096
	global_load_dword v16, v[4:5], off
	v_add_co_u32_e32 v4, vcc, s11, v40
	s_waitcnt vmcnt(16)
	v_mul_f32_e32 v150, v80, v6
	v_addc_co_u32_e32 v5, vcc, 0, v41, vcc
	s_waitcnt vmcnt(14)
	v_mul_f32_e32 v152, v81, v7
	global_load_dword v17, v[4:5], off offset:-4096
	global_load_dword v18, v[4:5], off
	s_nop 0
	global_load_dwordx4 v[4:7], v45, s[6:7] offset:144
	s_mov_b32 s11, 0x30000
	s_waitcnt vmcnt(16)
	v_mul_f32_e32 v154, v82, v24
	s_waitcnt vmcnt(15)
	v_mul_f32_e32 v156, v85, v25
	s_waitcnt vmcnt(14)
	v_mul_f32_e32 v158, v48, v26
	s_waitcnt vmcnt(13)
	v_mul_f32_e32 v160, v49, v27
	v_mov_b32_e32 v155, v154
	v_mov_b32_e32 v157, v156
	v_mov_b32_e32 v159, v158
	v_mov_b32_e32 v161, v160
	v_mov_b32_e32 v153, v152
	v_mov_b32_e32 v135, v134
	v_mov_b32_e32 v137, v136
	v_mov_b32_e32 v139, v138
	v_mov_b32_e32 v141, v140
	v_mov_b32_e32 v143, v142
	v_mov_b32_e32 v147, v146
	v_mov_b32_e32 v149, v148
	v_mov_b32_e32 v151, v150
	s_waitcnt vmcnt(0)
	v_mul_f32_e32 v162, v8, v4
	v_mul_f32_e32 v164, v9, v5
	v_mul_f32_e32 v166, v10, v6
	v_mul_f32_e32 v168, v11, v7
	global_load_dwordx4 v[4:7], v45, s[6:7] offset:160
	v_mov_b32_e32 v163, v162
	v_mov_b32_e32 v165, v164
	v_mov_b32_e32 v167, v166
	v_mov_b32_e32 v169, v168
	s_waitcnt vmcnt(0)
	v_mul_f32_e32 v170, v12, v4
	v_add_co_u32_e32 v4, vcc, s11, v40
	v_mul_f32_e32 v172, v13, v5
	s_nop 0
	v_addc_co_u32_e32 v5, vcc, 0, v41, vcc
	s_mov_b32 s11, 0x32000
	global_load_dword v8, v[4:5], off offset:-4096
	global_load_dword v9, v[4:5], off
	v_add_co_u32_e32 v4, vcc, s11, v40
	s_mov_b32 s11, 0x34000
	s_nop 0
	v_addc_co_u32_e32 v5, vcc, 0, v41, vcc
	global_load_dword v10, v[4:5], off offset:-4096
	global_load_dword v11, v[4:5], off
	v_add_co_u32_e32 v4, vcc, s11, v40
	v_mul_f32_e32 v174, v14, v6
	s_nop 0
	v_addc_co_u32_e32 v5, vcc, 0, v41, vcc
	global_load_dword v12, v[4:5], off offset:-4096
	global_load_dword v13, v[4:5], off
	v_add_co_u32_e32 v4, vcc, s74, v40
	v_mul_f32_e32 v176, v15, v7
	s_nop 0
	v_addc_co_u32_e32 v5, vcc, 0, v41, vcc
	global_load_dword v14, v[4:5], off offset:-4096
	global_load_dword v15, v[4:5], off
	s_nop 0
	global_load_dwordx4 v[4:7], v45, s[6:7] offset:176
	s_mov_b32 s11, 0x38000
	v_mov_b32_e32 v177, v176
	v_mov_b32_e32 v175, v174
	v_mov_b32_e32 v171, v170
	v_mov_b32_e32 v173, v172
	s_waitcnt vmcnt(0)
	v_mul_f32_e32 v178, v16, v4
	v_mul_f32_e32 v180, v17, v5
	v_mul_f32_e32 v182, v18, v6
	v_mul_f32_e32 v184, v8, v7
	global_load_dwordx4 v[4:7], v45, s[6:7] offset:192
	v_mov_b32_e32 v179, v178
	v_mov_b32_e32 v181, v180
	v_mov_b32_e32 v183, v182
	v_mov_b32_e32 v185, v184
	s_waitcnt vmcnt(0)
	v_mul_f32_e32 v186, v9, v4
	v_add_co_u32_e32 v4, vcc, s11, v40
	v_mul_f32_e32 v188, v10, v5
	s_nop 0
	v_addc_co_u32_e32 v5, vcc, 0, v41, vcc
	s_mov_b32 s11, 0x3a000
	v_mul_f32_e32 v190, v11, v6
	v_add_co_u32_e32 v6, vcc, s11, v40
	v_mul_f32_e32 v192, v12, v7
	s_nop 0
	v_addc_co_u32_e32 v7, vcc, 0, v41, vcc
	s_mov_b32 s11, 0x3c000
	v_add_co_u32_e32 v8, vcc, s11, v40
	s_mov_b32 s11, 0x3e000
	s_nop 0
	v_addc_co_u32_e32 v9, vcc, 0, v41, vcc
	v_add_co_u32_e32 v10, vcc, s11, v40
	v_readfirstlane_b32 s11, v0
	s_nop 0
	v_addc_co_u32_e32 v11, vcc, 0, v41, vcc
	global_load_dword v12, v[4:5], off offset:-4096
	global_load_dword v16, v[4:5], off
	global_load_dword v17, v[6:7], off offset:-4096
	global_load_dword v18, v[6:7], off
	global_load_dword v19, v[8:9], off offset:-4096
	s_nop 0
	global_load_dword v8, v[8:9], off
	s_nop 0
	global_load_dword v9, v[10:11], off offset:-4096
	s_nop 0
	global_load_dword v10, v[10:11], off
	s_nop 0
	global_load_dwordx4 v[4:7], v45, s[6:7] offset:208
	v_mov_b32_e32 v187, v186
	v_mov_b32_e32 v189, v188
	v_mov_b32_e32 v191, v190
	v_mov_b32_e32 v193, v192
	s_waitcnt vmcnt(0)
	v_mul_f32_e32 v194, v13, v4
	v_mul_f32_e32 v196, v14, v5
	v_mul_f32_e32 v198, v15, v6
	v_mul_f32_e32 v200, v12, v7
	global_load_dwordx4 v[4:7], v45, s[6:7] offset:224
	v_mov_b32_e32 v199, v198
	v_mov_b32_e32 v201, v200
	v_mov_b32_e32 v197, v196
	v_mov_b32_e32 v195, v194
	s_waitcnt vmcnt(0)
	v_mul_f32_e32 v202, v16, v4
	v_mul_f32_e32 v204, v17, v5
	v_mul_f32_e32 v206, v18, v6
	v_mul_f32_e32 v208, v19, v7
	global_load_dwordx4 v[4:7], v45, s[6:7] offset:240
	v_readfirstlane_b32 s7, v1
	s_mov_b32 s6, 0
	v_mov_b32_e32 v203, v202
	v_mov_b32_e32 v205, v204
	v_mov_b32_e32 v207, v206
	v_mov_b32_e32 v209, v208
	s_waitcnt vmcnt(0)
	v_mul_f32_e32 v210, v8, v4
	v_mul_f32_e32 v212, v9, v5
	v_lshlrev_b32_e32 v4, 9, v44
	v_mov_b32_e32 v5, v145
	v_lshl_add_u64 v[4:5], s[0:1], 0, v[4:5]
	s_add_u32 s0, s11, s4
	s_addc_u32 s1, s7, s5
	s_add_u32 s4, s0, s10
	s_addc_u32 s5, s1, 0
	s_lshl_b32 s26, s9, 1
	v_mul_f32_e32 v214, v10, v6
	v_mul_f32_e32 v216, v46, v7
	v_lshl_add_u64 v[4:5], v[4:5], 0, s[26:27]
	s_mov_b64 s[0:1], 0x2d80000
	v_lshl_add_u64 v[218:219], v[4:5], 0, s[0:1]
	v_mov_b32_e32 v211, v210
	v_mov_b32_e32 v213, v212
	v_mov_b32_e32 v215, v214
	v_mov_b32_e32 v217, v216
	v_lshlrev_b32_e32 v4, 5, v244
	global_load_dwordx4 v[8:11], v4, s[4:5]
	global_load_dwordx4 v[12:15], v4, s[4:5] offset:16
	v_add_u32_e32 v5, 0x8000, v4
	s_waitcnt vmcnt(0)
	ds_write_b128 v5, v[8:11]
	ds_write_b128 v5, v[12:15] offset:16
	s_waitcnt lgkmcnt(0)
	s_barrier
	v_mov_b32_e32 v80, 0x8000
.Lpool_c8:
	ds_read_b128 v[4:7], v80 offset:0
	ds_read_b128 v[8:11], v80 offset:16
	ds_read_b128 v[12:15], v80 offset:32
	ds_read_b128 v[16:19], v80 offset:48
	ds_read_b128 v[20:23], v80 offset:256
	ds_read_b128 v[24:27], v80 offset:272
	ds_read_b128 v[28:31], v80 offset:288
	ds_read_b128 v[32:35], v80 offset:304
	ds_read_b128 v[36:39], v80 offset:64
	ds_read_b128 v[40:43], v80 offset:80
	ds_read_b128 v[44:47], v80 offset:96
	ds_read_b128 v[48:51], v80 offset:112
	ds_read_b128 v[52:55], v80 offset:320
	ds_read_b128 v[56:59], v80 offset:336
	ds_read_b128 v[60:63], v80 offset:352
	ds_read_b128 v[64:67], v80 offset:368
	s_waitcnt lgkmcnt(8)
	v_mul_f32_e32 v68, v4, v88
	v_mul_f32_e32 v69, v20, v88
	v_fmac_f32_e32 v68, v5, v90
	v_fmac_f32_e32 v69, v21, v90
	v_fmac_f32_e32 v68, v6, v92
	v_fmac_f32_e32 v69, v22, v92
	v_fmac_f32_e32 v68, v7, v94
	v_fmac_f32_e32 v69, v23, v94
	v_fmac_f32_e32 v68, v8, v96
	v_fmac_f32_e32 v69, v24, v96
	v_fmac_f32_e32 v68, v9, v98
	v_fmac_f32_e32 v69, v25, v98
	v_fmac_f32_e32 v68, v10, v100
	v_fmac_f32_e32 v69, v26, v100
	v_fmac_f32_e32 v68, v11, v102
	v_fmac_f32_e32 v69, v27, v102
	v_fmac_f32_e32 v68, v12, v104
	v_fmac_f32_e32 v69, v28, v104
	v_fmac_f32_e32 v68, v13, v106
	v_fmac_f32_e32 v69, v29, v106
	v_fmac_f32_e32 v68, v14, v108
	v_fmac_f32_e32 v69, v30, v108
	v_fmac_f32_e32 v68, v15, v110
	v_fmac_f32_e32 v69, v31, v110
	v_fmac_f32_e32 v68, v16, v112
	v_fmac_f32_e32 v69, v32, v112
	v_fmac_f32_e32 v68, v17, v114
	v_fmac_f32_e32 v69, v33, v114
	v_fmac_f32_e32 v68, v18, v116
	v_fmac_f32_e32 v69, v34, v116
	v_fmac_f32_e32 v68, v19, v118
	v_fmac_f32_e32 v69, v35, v118
	ds_read_b128 v[4:7], v80 offset:128
	ds_read_b128 v[8:11], v80 offset:144
	ds_read_b128 v[12:15], v80 offset:160
	ds_read_b128 v[16:19], v80 offset:176
	ds_read_b128 v[20:23], v80 offset:384
	ds_read_b128 v[24:27], v80 offset:400
	ds_read_b128 v[28:31], v80 offset:416
	ds_read_b128 v[32:35], v80 offset:432
	s_waitcnt lgkmcnt(8)
	v_fmac_f32_e32 v68, v36, v120
	v_fmac_f32_e32 v69, v52, v120
	v_fmac_f32_e32 v68, v37, v122
	v_fmac_f32_e32 v69, v53, v122
	v_fmac_f32_e32 v68, v38, v124
	v_fmac_f32_e32 v69, v54, v124
	v_fmac_f32_e32 v68, v39, v126
	v_fmac_f32_e32 v69, v55, v126
	v_fmac_f32_e32 v68, v40, v128
	v_fmac_f32_e32 v69, v56, v128
	v_fmac_f32_e32 v68, v41, v130
	v_fmac_f32_e32 v69, v57, v130
	v_fmac_f32_e32 v68, v42, v132
	v_fmac_f32_e32 v69, v58, v132
	v_fmac_f32_e32 v68, v43, v134
	v_fmac_f32_e32 v69, v59, v134
	v_fmac_f32_e32 v68, v44, v136
	v_fmac_f32_e32 v69, v60, v136
	v_fmac_f32_e32 v68, v45, v138
	v_fmac_f32_e32 v69, v61, v138
	v_fmac_f32_e32 v68, v46, v140
	v_fmac_f32_e32 v69, v62, v140
	v_fmac_f32_e32 v68, v47, v142
	v_fmac_f32_e32 v69, v63, v142
	v_fmac_f32_e32 v68, v48, v146
	v_fmac_f32_e32 v69, v64, v146
	v_fmac_f32_e32 v68, v49, v148
	v_fmac_f32_e32 v69, v65, v148
	v_fmac_f32_e32 v68, v50, v150
	v_fmac_f32_e32 v69, v66, v150
	v_fmac_f32_e32 v68, v51, v152
	v_fmac_f32_e32 v69, v67, v152
	ds_read_b128 v[36:39], v80 offset:192
	ds_read_b128 v[40:43], v80 offset:208
	ds_read_b128 v[44:47], v80 offset:224
	ds_read_b128 v[48:51], v80 offset:240
	ds_read_b128 v[52:55], v80 offset:448
	ds_read_b128 v[56:59], v80 offset:464
	ds_read_b128 v[60:63], v80 offset:480
	ds_read_b128 v[64:67], v80 offset:496
	s_waitcnt lgkmcnt(8)
	v_fmac_f32_e32 v68, v4, v154
	v_fmac_f32_e32 v69, v20, v154
	v_fmac_f32_e32 v68, v5, v156
	v_fmac_f32_e32 v69, v21, v156
	v_fmac_f32_e32 v68, v6, v158
	v_fmac_f32_e32 v69, v22, v158
	v_fmac_f32_e32 v68, v7, v160
	v_fmac_f32_e32 v69, v23, v160
	v_fmac_f32_e32 v68, v8, v162
	v_fmac_f32_e32 v69, v24, v162
	v_fmac_f32_e32 v68, v9, v164
	v_fmac_f32_e32 v69, v25, v164
	v_fmac_f32_e32 v68, v10, v166
	v_fmac_f32_e32 v69, v26, v166
	v_fmac_f32_e32 v68, v11, v168
	v_fmac_f32_e32 v69, v27, v168
	v_fmac_f32_e32 v68, v12, v170
	v_fmac_f32_e32 v69, v28, v170
	v_fmac_f32_e32 v68, v13, v172
	v_fmac_f32_e32 v69, v29, v172
	v_fmac_f32_e32 v68, v14, v174
	v_fmac_f32_e32 v69, v30, v174
	v_fmac_f32_e32 v68, v15, v176
	v_fmac_f32_e32 v69, v31, v176
	v_fmac_f32_e32 v68, v16, v178
	v_fmac_f32_e32 v69, v32, v178
	v_fmac_f32_e32 v68, v17, v180
	v_fmac_f32_e32 v69, v33, v180
	v_fmac_f32_e32 v68, v18, v182
	v_fmac_f32_e32 v69, v34, v182
	v_fmac_f32_e32 v68, v19, v184
	v_fmac_f32_e32 v69, v35, v184
	ds_read_b128 v[4:7], v80 offset:512
	ds_read_b128 v[8:11], v80 offset:528
	ds_read_b128 v[12:15], v80 offset:544
	ds_read_b128 v[16:19], v80 offset:560
	ds_read_b128 v[20:23], v80 offset:768
	ds_read_b128 v[24:27], v80 offset:784
	ds_read_b128 v[28:31], v80 offset:800
	ds_read_b128 v[32:35], v80 offset:816
	s_waitcnt lgkmcnt(8)
	v_fmac_f32_e32 v68, v36, v186
	v_fmac_f32_e32 v69, v52, v186
	v_fmac_f32_e32 v68, v37, v188
	v_fmac_f32_e32 v69, v53, v188
	v_fmac_f32_e32 v68, v38, v190
	v_fmac_f32_e32 v69, v54, v190
	v_fmac_f32_e32 v68, v39, v192
	v_fmac_f32_e32 v69, v55, v192
	v_fmac_f32_e32 v68, v40, v194
	v_fmac_f32_e32 v69, v56, v194
	v_fmac_f32_e32 v68, v41, v196
	v_fmac_f32_e32 v69, v57, v196
	v_fmac_f32_e32 v68, v42, v198
	v_fmac_f32_e32 v69, v58, v198
	v_fmac_f32_e32 v68, v43, v200
	v_fmac_f32_e32 v69, v59, v200
	v_fmac_f32_e32 v68, v44, v202
	v_fmac_f32_e32 v69, v60, v202
	v_fmac_f32_e32 v68, v45, v204
	v_fmac_f32_e32 v69, v61, v204
	v_fmac_f32_e32 v68, v46, v206
	v_fmac_f32_e32 v69, v62, v206
	v_fmac_f32_e32 v68, v47, v208
	v_fmac_f32_e32 v69, v63, v208
	v_fmac_f32_e32 v68, v48, v210
	v_fmac_f32_e32 v69, v64, v210
	v_fmac_f32_e32 v68, v49, v212
	v_fmac_f32_e32 v69, v65, v212
	v_fmac_f32_e32 v68, v50, v214
	v_fmac_f32_e32 v69, v66, v214
	v_fmac_f32_e32 v68, v51, v216
	v_fmac_f32_e32 v69, v67, v216
	ds_read_b128 v[36:39], v80 offset:576
	ds_read_b128 v[40:43], v80 offset:592
	ds_read_b128 v[44:47], v80 offset:608
	ds_read_b128 v[48:51], v80 offset:624
	ds_read_b128 v[52:55], v80 offset:832
	ds_read_b128 v[56:59], v80 offset:848
	ds_read_b128 v[60:63], v80 offset:864
	ds_read_b128 v[64:67], v80 offset:880
	s_waitcnt lgkmcnt(8)
	v_mul_f32_e32 v70, v4, v88
	v_mul_f32_e32 v71, v20, v88
	v_fmac_f32_e32 v70, v5, v90
	v_fmac_f32_e32 v71, v21, v90
	v_fmac_f32_e32 v70, v6, v92
	v_fmac_f32_e32 v71, v22, v92
	v_fmac_f32_e32 v70, v7, v94
	v_fmac_f32_e32 v71, v23, v94
	v_fmac_f32_e32 v70, v8, v96
	v_fmac_f32_e32 v71, v24, v96
	v_fmac_f32_e32 v70, v9, v98
	v_fmac_f32_e32 v71, v25, v98
	v_fmac_f32_e32 v70, v10, v100
	v_fmac_f32_e32 v71, v26, v100
	v_fmac_f32_e32 v70, v11, v102
	v_fmac_f32_e32 v71, v27, v102
	v_fmac_f32_e32 v70, v12, v104
	v_fmac_f32_e32 v71, v28, v104
	v_fmac_f32_e32 v70, v13, v106
	v_fmac_f32_e32 v71, v29, v106
	v_fmac_f32_e32 v70, v14, v108
	v_fmac_f32_e32 v71, v30, v108
	v_fmac_f32_e32 v70, v15, v110
	v_fmac_f32_e32 v71, v31, v110
	v_fmac_f32_e32 v70, v16, v112
	v_fmac_f32_e32 v71, v32, v112
	v_fmac_f32_e32 v70, v17, v114
	v_fmac_f32_e32 v71, v33, v114
	v_fmac_f32_e32 v70, v18, v116
	v_fmac_f32_e32 v71, v34, v116
	v_fmac_f32_e32 v70, v19, v118
	v_fmac_f32_e32 v71, v35, v118
	ds_read_b128 v[4:7], v80 offset:640
	ds_read_b128 v[8:11], v80 offset:656
	ds_read_b128 v[12:15], v80 offset:672
	ds_read_b128 v[16:19], v80 offset:688
	ds_read_b128 v[20:23], v80 offset:896
	ds_read_b128 v[24:27], v80 offset:912
	ds_read_b128 v[28:31], v80 offset:928
	ds_read_b128 v[32:35], v80 offset:944
	s_waitcnt lgkmcnt(8)
	v_fmac_f32_e32 v70, v36, v120
	v_fmac_f32_e32 v71, v52, v120
	v_fmac_f32_e32 v70, v37, v122
	v_fmac_f32_e32 v71, v53, v122
	v_fmac_f32_e32 v70, v38, v124
	v_fmac_f32_e32 v71, v54, v124
	v_fmac_f32_e32 v70, v39, v126
	v_fmac_f32_e32 v71, v55, v126
	v_fmac_f32_e32 v70, v40, v128
	v_fmac_f32_e32 v71, v56, v128
	v_fmac_f32_e32 v70, v41, v130
	v_fmac_f32_e32 v71, v57, v130
	v_fmac_f32_e32 v70, v42, v132
	v_fmac_f32_e32 v71, v58, v132
	v_fmac_f32_e32 v70, v43, v134
	v_fmac_f32_e32 v71, v59, v134
	v_fmac_f32_e32 v70, v44, v136
	v_fmac_f32_e32 v71, v60, v136
	v_fmac_f32_e32 v70, v45, v138
	v_fmac_f32_e32 v71, v61, v138
	v_fmac_f32_e32 v70, v46, v140
	v_fmac_f32_e32 v71, v62, v140
	v_fmac_f32_e32 v70, v47, v142
	v_fmac_f32_e32 v71, v63, v142
	v_fmac_f32_e32 v70, v48, v146
	v_fmac_f32_e32 v71, v64, v146
	v_fmac_f32_e32 v70, v49, v148
	v_fmac_f32_e32 v71, v65, v148
	v_fmac_f32_e32 v70, v50, v150
	v_fmac_f32_e32 v71, v66, v150
	v_fmac_f32_e32 v70, v51, v152
	v_fmac_f32_e32 v71, v67, v152
	ds_read_b128 v[36:39], v80 offset:704
	ds_read_b128 v[40:43], v80 offset:720
	ds_read_b128 v[44:47], v80 offset:736
	ds_read_b128 v[48:51], v80 offset:752
	ds_read_b128 v[52:55], v80 offset:960
	ds_read_b128 v[56:59], v80 offset:976
	ds_read_b128 v[60:63], v80 offset:992
	ds_read_b128 v[64:67], v80 offset:1008
	s_waitcnt lgkmcnt(8)
	v_fmac_f32_e32 v70, v4, v154
	v_fmac_f32_e32 v71, v20, v154
	v_fmac_f32_e32 v70, v5, v156
	v_fmac_f32_e32 v71, v21, v156
	v_fmac_f32_e32 v70, v6, v158
	v_fmac_f32_e32 v71, v22, v158
	v_fmac_f32_e32 v70, v7, v160
	v_fmac_f32_e32 v71, v23, v160
	v_fmac_f32_e32 v70, v8, v162
	v_fmac_f32_e32 v71, v24, v162
	v_fmac_f32_e32 v70, v9, v164
	v_fmac_f32_e32 v71, v25, v164
	v_fmac_f32_e32 v70, v10, v166
	v_fmac_f32_e32 v71, v26, v166
	v_fmac_f32_e32 v70, v11, v168
	v_fmac_f32_e32 v71, v27, v168
	v_fmac_f32_e32 v70, v12, v170
	v_fmac_f32_e32 v71, v28, v170
	v_fmac_f32_e32 v70, v13, v172
	v_fmac_f32_e32 v71, v29, v172
	v_fmac_f32_e32 v70, v14, v174
	v_fmac_f32_e32 v71, v30, v174
	v_fmac_f32_e32 v70, v15, v176
	v_fmac_f32_e32 v71, v31, v176
	v_fmac_f32_e32 v70, v16, v178
	v_fmac_f32_e32 v71, v32, v178
	v_fmac_f32_e32 v70, v17, v180
	v_fmac_f32_e32 v71, v33, v180
	v_fmac_f32_e32 v70, v18, v182
	v_fmac_f32_e32 v71, v34, v182
	v_fmac_f32_e32 v70, v19, v184
	v_fmac_f32_e32 v71, v35, v184
	ds_read_b128 v[4:7], v80 offset:1024
	ds_read_b128 v[8:11], v80 offset:1040
	ds_read_b128 v[12:15], v80 offset:1056
	ds_read_b128 v[16:19], v80 offset:1072
	ds_read_b128 v[20:23], v80 offset:1280
	ds_read_b128 v[24:27], v80 offset:1296
	ds_read_b128 v[28:31], v80 offset:1312
	ds_read_b128 v[32:35], v80 offset:1328
	s_waitcnt lgkmcnt(8)
	v_fmac_f32_e32 v70, v36, v186
	v_fmac_f32_e32 v71, v52, v186
	v_fmac_f32_e32 v70, v37, v188
	v_fmac_f32_e32 v71, v53, v188
	v_fmac_f32_e32 v70, v38, v190
	v_fmac_f32_e32 v71, v54, v190
	v_fmac_f32_e32 v70, v39, v192
	v_fmac_f32_e32 v71, v55, v192
	v_fmac_f32_e32 v70, v40, v194
	v_fmac_f32_e32 v71, v56, v194
	v_fmac_f32_e32 v70, v41, v196
	v_fmac_f32_e32 v71, v57, v196
	v_fmac_f32_e32 v70, v42, v198
	v_fmac_f32_e32 v71, v58, v198
	v_fmac_f32_e32 v70, v43, v200
	v_fmac_f32_e32 v71, v59, v200
	v_fmac_f32_e32 v70, v44, v202
	v_fmac_f32_e32 v71, v60, v202
	v_fmac_f32_e32 v70, v45, v204
	v_fmac_f32_e32 v71, v61, v204
	v_fmac_f32_e32 v70, v46, v206
	v_fmac_f32_e32 v71, v62, v206
	v_fmac_f32_e32 v70, v47, v208
	v_fmac_f32_e32 v71, v63, v208
	v_fmac_f32_e32 v70, v48, v210
	v_fmac_f32_e32 v71, v64, v210
	v_fmac_f32_e32 v70, v49, v212
	v_fmac_f32_e32 v71, v65, v212
	v_fmac_f32_e32 v70, v50, v214
	v_fmac_f32_e32 v71, v66, v214
	v_fmac_f32_e32 v70, v51, v216
	v_fmac_f32_e32 v71, v67, v216
	ds_read_b128 v[36:39], v80 offset:1088
	ds_read_b128 v[40:43], v80 offset:1104
	ds_read_b128 v[44:47], v80 offset:1120
	ds_read_b128 v[48:51], v80 offset:1136
	ds_read_b128 v[52:55], v80 offset:1344
	ds_read_b128 v[56:59], v80 offset:1360
	ds_read_b128 v[60:63], v80 offset:1376
	ds_read_b128 v[64:67], v80 offset:1392
	s_waitcnt lgkmcnt(8)
	v_mul_f32_e32 v72, v4, v88
	v_mul_f32_e32 v73, v20, v88
	v_fmac_f32_e32 v72, v5, v90
	v_fmac_f32_e32 v73, v21, v90
	v_fmac_f32_e32 v72, v6, v92
	v_fmac_f32_e32 v73, v22, v92
	v_fmac_f32_e32 v72, v7, v94
	v_fmac_f32_e32 v73, v23, v94
	v_fmac_f32_e32 v72, v8, v96
	v_fmac_f32_e32 v73, v24, v96
	v_fmac_f32_e32 v72, v9, v98
	v_fmac_f32_e32 v73, v25, v98
	v_fmac_f32_e32 v72, v10, v100
	v_fmac_f32_e32 v73, v26, v100
	v_fmac_f32_e32 v72, v11, v102
	v_fmac_f32_e32 v73, v27, v102
	v_fmac_f32_e32 v72, v12, v104
	v_fmac_f32_e32 v73, v28, v104
	v_fmac_f32_e32 v72, v13, v106
	v_fmac_f32_e32 v73, v29, v106
	v_fmac_f32_e32 v72, v14, v108
	v_fmac_f32_e32 v73, v30, v108
	v_fmac_f32_e32 v72, v15, v110
	v_fmac_f32_e32 v73, v31, v110
	v_fmac_f32_e32 v72, v16, v112
	v_fmac_f32_e32 v73, v32, v112
	v_fmac_f32_e32 v72, v17, v114
	v_fmac_f32_e32 v73, v33, v114
	v_fmac_f32_e32 v72, v18, v116
	v_fmac_f32_e32 v73, v34, v116
	v_fmac_f32_e32 v72, v19, v118
	v_fmac_f32_e32 v73, v35, v118
	ds_read_b128 v[4:7], v80 offset:1152
	ds_read_b128 v[8:11], v80 offset:1168
	ds_read_b128 v[12:15], v80 offset:1184
	ds_read_b128 v[16:19], v80 offset:1200
	ds_read_b128 v[20:23], v80 offset:1408
	ds_read_b128 v[24:27], v80 offset:1424
	ds_read_b128 v[28:31], v80 offset:1440
	ds_read_b128 v[32:35], v80 offset:1456
	s_waitcnt lgkmcnt(8)
	v_fmac_f32_e32 v72, v36, v120
	v_fmac_f32_e32 v73, v52, v120
	v_fmac_f32_e32 v72, v37, v122
	v_fmac_f32_e32 v73, v53, v122
	v_fmac_f32_e32 v72, v38, v124
	v_fmac_f32_e32 v73, v54, v124
	v_fmac_f32_e32 v72, v39, v126
	v_fmac_f32_e32 v73, v55, v126
	v_fmac_f32_e32 v72, v40, v128
	v_fmac_f32_e32 v73, v56, v128
	v_fmac_f32_e32 v72, v41, v130
	v_fmac_f32_e32 v73, v57, v130
	v_fmac_f32_e32 v72, v42, v132
	v_fmac_f32_e32 v73, v58, v132
	v_fmac_f32_e32 v72, v43, v134
	v_fmac_f32_e32 v73, v59, v134
	v_fmac_f32_e32 v72, v44, v136
	v_fmac_f32_e32 v73, v60, v136
	v_fmac_f32_e32 v72, v45, v138
	v_fmac_f32_e32 v73, v61, v138
	v_fmac_f32_e32 v72, v46, v140
	v_fmac_f32_e32 v73, v62, v140
	v_fmac_f32_e32 v72, v47, v142
	v_fmac_f32_e32 v73, v63, v142
	v_fmac_f32_e32 v72, v48, v146
	v_fmac_f32_e32 v73, v64, v146
	v_fmac_f32_e32 v72, v49, v148
	v_fmac_f32_e32 v73, v65, v148
	v_fmac_f32_e32 v72, v50, v150
	v_fmac_f32_e32 v73, v66, v150
	v_fmac_f32_e32 v72, v51, v152
	v_fmac_f32_e32 v73, v67, v152
	ds_read_b128 v[36:39], v80 offset:1216
	ds_read_b128 v[40:43], v80 offset:1232
	ds_read_b128 v[44:47], v80 offset:1248
	ds_read_b128 v[48:51], v80 offset:1264
	ds_read_b128 v[52:55], v80 offset:1472
	ds_read_b128 v[56:59], v80 offset:1488
	ds_read_b128 v[60:63], v80 offset:1504
	ds_read_b128 v[64:67], v80 offset:1520
	s_waitcnt lgkmcnt(8)
	v_fmac_f32_e32 v72, v4, v154
	v_fmac_f32_e32 v73, v20, v154
	v_fmac_f32_e32 v72, v5, v156
	v_fmac_f32_e32 v73, v21, v156
	v_fmac_f32_e32 v72, v6, v158
	v_fmac_f32_e32 v73, v22, v158
	v_fmac_f32_e32 v72, v7, v160
	v_fmac_f32_e32 v73, v23, v160
	v_fmac_f32_e32 v72, v8, v162
	v_fmac_f32_e32 v73, v24, v162
	v_fmac_f32_e32 v72, v9, v164
	v_fmac_f32_e32 v73, v25, v164
	v_fmac_f32_e32 v72, v10, v166
	v_fmac_f32_e32 v73, v26, v166
	v_fmac_f32_e32 v72, v11, v168
	v_fmac_f32_e32 v73, v27, v168
	v_fmac_f32_e32 v72, v12, v170
	v_fmac_f32_e32 v73, v28, v170
	v_fmac_f32_e32 v72, v13, v172
	v_fmac_f32_e32 v73, v29, v172
	v_fmac_f32_e32 v72, v14, v174
	v_fmac_f32_e32 v73, v30, v174
	v_fmac_f32_e32 v72, v15, v176
	v_fmac_f32_e32 v73, v31, v176
	v_fmac_f32_e32 v72, v16, v178
	v_fmac_f32_e32 v73, v32, v178
	v_fmac_f32_e32 v72, v17, v180
	v_fmac_f32_e32 v73, v33, v180
	v_fmac_f32_e32 v72, v18, v182
	v_fmac_f32_e32 v73, v34, v182
	v_fmac_f32_e32 v72, v19, v184
	v_fmac_f32_e32 v73, v35, v184
	ds_read_b128 v[4:7], v80 offset:1536
	ds_read_b128 v[8:11], v80 offset:1552
	ds_read_b128 v[12:15], v80 offset:1568
	ds_read_b128 v[16:19], v80 offset:1584
	ds_read_b128 v[20:23], v80 offset:1792
	ds_read_b128 v[24:27], v80 offset:1808
	ds_read_b128 v[28:31], v80 offset:1824
	ds_read_b128 v[32:35], v80 offset:1840
	s_waitcnt lgkmcnt(8)
	v_fmac_f32_e32 v72, v36, v186
	v_fmac_f32_e32 v73, v52, v186
	v_fmac_f32_e32 v72, v37, v188
	v_fmac_f32_e32 v73, v53, v188
	v_fmac_f32_e32 v72, v38, v190
	v_fmac_f32_e32 v73, v54, v190
	v_fmac_f32_e32 v72, v39, v192
	v_fmac_f32_e32 v73, v55, v192
	v_fmac_f32_e32 v72, v40, v194
	v_fmac_f32_e32 v73, v56, v194
	v_fmac_f32_e32 v72, v41, v196
	v_fmac_f32_e32 v73, v57, v196
	v_fmac_f32_e32 v72, v42, v198
	v_fmac_f32_e32 v73, v58, v198
	v_fmac_f32_e32 v72, v43, v200
	v_fmac_f32_e32 v73, v59, v200
	v_fmac_f32_e32 v72, v44, v202
	v_fmac_f32_e32 v73, v60, v202
	v_fmac_f32_e32 v72, v45, v204
	v_fmac_f32_e32 v73, v61, v204
	v_fmac_f32_e32 v72, v46, v206
	v_fmac_f32_e32 v73, v62, v206
	v_fmac_f32_e32 v72, v47, v208
	v_fmac_f32_e32 v73, v63, v208
	v_fmac_f32_e32 v72, v48, v210
	v_fmac_f32_e32 v73, v64, v210
	v_fmac_f32_e32 v72, v49, v212
	v_fmac_f32_e32 v73, v65, v212
	v_fmac_f32_e32 v72, v50, v214
	v_fmac_f32_e32 v73, v66, v214
	v_fmac_f32_e32 v72, v51, v216
	v_fmac_f32_e32 v73, v67, v216
	ds_read_b128 v[36:39], v80 offset:1600
	ds_read_b128 v[40:43], v80 offset:1616
	ds_read_b128 v[44:47], v80 offset:1632
	ds_read_b128 v[48:51], v80 offset:1648
	ds_read_b128 v[52:55], v80 offset:1856
	ds_read_b128 v[56:59], v80 offset:1872
	ds_read_b128 v[60:63], v80 offset:1888
	ds_read_b128 v[64:67], v80 offset:1904
	s_waitcnt lgkmcnt(8)
	v_mul_f32_e32 v74, v4, v88
	v_mul_f32_e32 v75, v20, v88
	v_fmac_f32_e32 v74, v5, v90
	v_fmac_f32_e32 v75, v21, v90
	v_fmac_f32_e32 v74, v6, v92
	v_fmac_f32_e32 v75, v22, v92
	v_fmac_f32_e32 v74, v7, v94
	v_fmac_f32_e32 v75, v23, v94
	v_fmac_f32_e32 v74, v8, v96
	v_fmac_f32_e32 v75, v24, v96
	v_fmac_f32_e32 v74, v9, v98
	v_fmac_f32_e32 v75, v25, v98
	v_fmac_f32_e32 v74, v10, v100
	v_fmac_f32_e32 v75, v26, v100
	v_fmac_f32_e32 v74, v11, v102
	v_fmac_f32_e32 v75, v27, v102
	v_fmac_f32_e32 v74, v12, v104
	v_fmac_f32_e32 v75, v28, v104
	v_fmac_f32_e32 v74, v13, v106
	v_fmac_f32_e32 v75, v29, v106
	v_fmac_f32_e32 v74, v14, v108
	v_fmac_f32_e32 v75, v30, v108
	v_fmac_f32_e32 v74, v15, v110
	v_fmac_f32_e32 v75, v31, v110
	v_fmac_f32_e32 v74, v16, v112
	v_fmac_f32_e32 v75, v32, v112
	v_fmac_f32_e32 v74, v17, v114
	v_fmac_f32_e32 v75, v33, v114
	v_fmac_f32_e32 v74, v18, v116
	v_fmac_f32_e32 v75, v34, v116
	v_fmac_f32_e32 v74, v19, v118
	v_fmac_f32_e32 v75, v35, v118
	ds_read_b128 v[4:7], v80 offset:1664
	ds_read_b128 v[8:11], v80 offset:1680
	ds_read_b128 v[12:15], v80 offset:1696
	ds_read_b128 v[16:19], v80 offset:1712
	ds_read_b128 v[20:23], v80 offset:1920
	ds_read_b128 v[24:27], v80 offset:1936
	ds_read_b128 v[28:31], v80 offset:1952
	ds_read_b128 v[32:35], v80 offset:1968
	s_waitcnt lgkmcnt(8)
	v_fmac_f32_e32 v74, v36, v120
	v_fmac_f32_e32 v75, v52, v120
	v_fmac_f32_e32 v74, v37, v122
	v_fmac_f32_e32 v75, v53, v122
	v_fmac_f32_e32 v74, v38, v124
	v_fmac_f32_e32 v75, v54, v124
	v_fmac_f32_e32 v74, v39, v126
	v_fmac_f32_e32 v75, v55, v126
	v_fmac_f32_e32 v74, v40, v128
	v_fmac_f32_e32 v75, v56, v128
	v_fmac_f32_e32 v74, v41, v130
	v_fmac_f32_e32 v75, v57, v130
	v_fmac_f32_e32 v74, v42, v132
	v_fmac_f32_e32 v75, v58, v132
	v_fmac_f32_e32 v74, v43, v134
	v_fmac_f32_e32 v75, v59, v134
	v_fmac_f32_e32 v74, v44, v136
	v_fmac_f32_e32 v75, v60, v136
	v_fmac_f32_e32 v74, v45, v138
	v_fmac_f32_e32 v75, v61, v138
	v_fmac_f32_e32 v74, v46, v140
	v_fmac_f32_e32 v75, v62, v140
	v_fmac_f32_e32 v74, v47, v142
	v_fmac_f32_e32 v75, v63, v142
	v_fmac_f32_e32 v74, v48, v146
	v_fmac_f32_e32 v75, v64, v146
	v_fmac_f32_e32 v74, v49, v148
	v_fmac_f32_e32 v75, v65, v148
	v_fmac_f32_e32 v74, v50, v150
	v_fmac_f32_e32 v75, v66, v150
	v_fmac_f32_e32 v74, v51, v152
	v_fmac_f32_e32 v75, v67, v152
	ds_read_b128 v[36:39], v80 offset:1728
	ds_read_b128 v[40:43], v80 offset:1744
	ds_read_b128 v[44:47], v80 offset:1760
	ds_read_b128 v[48:51], v80 offset:1776
	ds_read_b128 v[52:55], v80 offset:1984
	ds_read_b128 v[56:59], v80 offset:2000
	ds_read_b128 v[60:63], v80 offset:2016
	ds_read_b128 v[64:67], v80 offset:2032
	s_waitcnt lgkmcnt(8)
	v_fmac_f32_e32 v74, v4, v154
	v_fmac_f32_e32 v75, v20, v154
	v_fmac_f32_e32 v74, v5, v156
	v_fmac_f32_e32 v75, v21, v156
	v_fmac_f32_e32 v74, v6, v158
	v_fmac_f32_e32 v75, v22, v158
	v_fmac_f32_e32 v74, v7, v160
	v_fmac_f32_e32 v75, v23, v160
	v_fmac_f32_e32 v74, v8, v162
	v_fmac_f32_e32 v75, v24, v162
	v_fmac_f32_e32 v74, v9, v164
	v_fmac_f32_e32 v75, v25, v164
	v_fmac_f32_e32 v74, v10, v166
	v_fmac_f32_e32 v75, v26, v166
	v_fmac_f32_e32 v74, v11, v168
	v_fmac_f32_e32 v75, v27, v168
	v_fmac_f32_e32 v74, v12, v170
	v_fmac_f32_e32 v75, v28, v170
	v_fmac_f32_e32 v74, v13, v172
	v_fmac_f32_e32 v75, v29, v172
	v_fmac_f32_e32 v74, v14, v174
	v_fmac_f32_e32 v75, v30, v174
	v_fmac_f32_e32 v74, v15, v176
	v_fmac_f32_e32 v75, v31, v176
	v_fmac_f32_e32 v74, v16, v178
	v_fmac_f32_e32 v75, v32, v178
	v_fmac_f32_e32 v74, v17, v180
	v_fmac_f32_e32 v75, v33, v180
	v_fmac_f32_e32 v74, v18, v182
	v_fmac_f32_e32 v75, v34, v182
	v_fmac_f32_e32 v74, v19, v184
	v_fmac_f32_e32 v75, v35, v184
	s_waitcnt lgkmcnt(0)
	v_fmac_f32_e32 v74, v36, v186
	v_fmac_f32_e32 v75, v52, v186
	v_fmac_f32_e32 v74, v37, v188
	v_fmac_f32_e32 v75, v53, v188
	v_fmac_f32_e32 v74, v38, v190
	v_fmac_f32_e32 v75, v54, v190
	v_fmac_f32_e32 v74, v39, v192
	v_fmac_f32_e32 v75, v55, v192
	v_fmac_f32_e32 v74, v40, v194
	v_fmac_f32_e32 v75, v56, v194
	v_fmac_f32_e32 v74, v41, v196
	v_fmac_f32_e32 v75, v57, v196
	v_fmac_f32_e32 v74, v42, v198
	v_fmac_f32_e32 v75, v58, v198
	v_fmac_f32_e32 v74, v43, v200
	v_fmac_f32_e32 v75, v59, v200
	v_fmac_f32_e32 v74, v44, v202
	v_fmac_f32_e32 v75, v60, v202
	v_fmac_f32_e32 v74, v45, v204
	v_fmac_f32_e32 v75, v61, v204
	v_fmac_f32_e32 v74, v46, v206
	v_fmac_f32_e32 v75, v62, v206
	v_fmac_f32_e32 v74, v47, v208
	v_fmac_f32_e32 v75, v63, v208
	v_fmac_f32_e32 v74, v48, v210
	v_fmac_f32_e32 v75, v64, v210
	v_fmac_f32_e32 v74, v49, v212
	v_fmac_f32_e32 v75, v65, v212
	v_fmac_f32_e32 v74, v50, v214
	v_fmac_f32_e32 v75, v66, v214
	v_fmac_f32_e32 v74, v51, v216
	v_fmac_f32_e32 v75, v67, v216
	s_lshl_b32 s26, s6, 4
	v_cvt_pk_bf16_f32 v68, v68, v69
	v_cvt_pk_bf16_f32 v69, v70, v71
	v_cvt_pk_bf16_f32 v70, v72, v73
	v_cvt_pk_bf16_f32 v71, v74, v75
	v_lshl_add_u64 v[76:77], v[218:219], 0, s[26:27]
	v_add_u32_e32 v80, 0x800, v80
	s_add_i32 s6, s6, 1
	global_store_dwordx4 v[76:77], v[68:71], off
	s_cmp_lg_u32 s6, 8
	s_cbranch_scc1 .Lpool_c8
	s_barrier
	s_add_i32 s8, s8, s64
	s_cmpk_gt_i32 s8, 0xff
	s_cbranch_scc0 .LBB0_694
